# v62 + hgC: loop rotation fix + deferred queue draw + 8 per-class queues
# speedup vs baseline: 1.0227x; 1.0001x over previous
; __device__ __forceinline__ void hgC_loop(Frame& F, unsigned* ctr) {
;     ...
;     if (tid == 0) { slot[0] = (int)__hip_atomic_fetch_add(ctr, 1u, __ATOMIC_RELAXED, __HIP_MEMORY_SCOPE_AGENT); slot[1] = (int)__hip_atomic_fetch_add(ctr, 1u, __ATOMIC_RELAXED, __HIP_MEMORY_SCOPE_AGENT); }
;     __syncthreads();
;     int item = slot[0], nxt = slot[1], par = 0;
;     if (item >= 1024) return;
.LBB0_684:
	s_add_u32 s4, s50, 0x8000
	s_addc_u32 s5, s51, 0
	s_and_b32 s3, s2, 7
	s_lshl_b32 s30, s3, 7
	s_lshl_b32 s3, s3, 8
	s_add_u32 s4, s4, s3
	s_addc_u32 s5, s5, 0
	v_mov_b32_e32 v235, 0x400
	s_waitcnt vmcnt(0)
	s_barrier
	s_and_saveexec_b64 s[0:1], s[92:93]
	s_cbranch_execz .LBB0_690
	s_mov_b64 s[12:13], exec
	v_mbcnt_lo_u32_b32 v2, s12, 0
	v_mbcnt_hi_u32_b32 v2, s13, v2
	v_cmp_eq_u32_e32 vcc, 0, v2
	s_and_saveexec_b64 s[10:11], vcc
	s_cbranch_execz .LBB0_687
	s_bcnt1_i32_b64 s3, s[12:13]
	v_mov_b32_e32 v3, 0
	v_mov_b32_e32 v4, s3
	global_atomic_add v3, v3, v4, s[4:5] sc0
.LBB0_687:
	s_or_b64 exec, exec, s[10:11]
	s_waitcnt vmcnt(0)
	v_readfirstlane_b32 s3, v3
	s_mov_b64 s[10:11], exec
	s_nop 0
	v_add_u32_e32 v3, s3, v2
	v_mov_b32_e32 v2, 0
	v_cmp_gt_u32_e32 vcc, 0x80, v3
	v_add_u32_e32 v3, s30, v3
	s_nop 1
	v_cndmask_b32_e32 v3, v235, v3, vcc
	ds_write_b32 v2, v3 offset:53248
	v_mbcnt_lo_u32_b32 v3, s10, 0
	v_mbcnt_hi_u32_b32 v3, s11, v3
	v_cmp_eq_u32_e32 vcc, 0, v3
	s_and_saveexec_b64 s[12:13], vcc
	s_cbranch_execz .LBB0_689
	s_bcnt1_i32_b64 s3, s[10:11]
	v_mov_b32_e32 v4, s3
	global_atomic_add v4, v2, v4, s[4:5] sc0
.LBB0_689:
	s_or_b64 exec, exec, s[12:13]
	s_waitcnt vmcnt(0)
	v_readfirstlane_b32 s3, v4
	s_nop 1
	v_add_u32_e32 v3, s3, v3
	v_cmp_gt_u32_e32 vcc, 0x80, v3
	v_add_u32_e32 v3, s30, v3
	s_nop 1
	v_cndmask_b32_e32 v3, v235, v3, vcc
	ds_write_b32 v2, v3 offset:53252

; __device__ __forceinline__ void hgC_loop(Frame& F, unsigned* ctr) {
;     ...
;         if (tid == 0) slot[par] = (int)__hip_atomic_fetch_add(ctr, 1u, __ATOMIC_RELAXED, __HIP_MEMORY_SCOPE_AGENT);
;         if (nxt < 1024) HGC_FETCH(nxt);
;         __syncthreads();
;         const int nn = slot[par];
my_hgq_w:
	v_lshrrev_b32_e32 v234, 7, v236
	v_cmp_eq_u32_e64 s[24:25], 0, v234
	v_add_u32_e32 v236, s30, v236
	s_nop 1
	v_cndmask_b32_e64 v236, v235, v236, s[24:25]
	ds_write_b32 v55, v236 offset:53256
